# stack5 + P3 second MLP layer moved from VALU pk_fma to f32 MFMA 16x16x4 (f32 operands/accumulate), w2 loads via saddr, issued before the barrier
# speedup vs baseline: 1.0052x; 1.0051x over previous
.LBB0_570:
	s_cmp_lt_i32 s88, 4
	s_cselect_b64 s[0:1], -1, 0
	s_and_b64 s[2:3], s[0:1], s[2:3]
	s_andn2_b64 vcc, exec, s[2:3]
	s_cbranch_vccnz .LBB0_586
	s_cmpk_gt_i32 s78, 0xff
	s_cbranch_scc1 .LBB0_586
	s_waitcnt vmcnt(0)
	v_and_b32_e32 v4, 0xff, v0
	v_lshl_add_u32 v8, v4, 6, 0
	v_mul_i32_i24_e32 v9, 0xffffffc4, v4
	v_mov_b32_e32 v5, 0
	v_lshlrev_b32_e32 v4, 1, v4
	v_lshl_add_u64 v[6:7], s[76:77], 0, v[4:5]
	v_or_b32_e32 v4, 0x200, v0
	s_load_dwordx2 s[6:7], s[80:81], 0x30
	s_load_dwordx2 s[8:9], s[80:81], 0x48
	v_lshrrev_b32_e32 v17, 8, v4
	v_or_b32_e32 v4, 0x600, v0
	v_lshrrev_b32_e32 v20, 8, v4
	v_or_b32_e32 v4, 0xa00, v0
	v_lshrrev_b32_e32 v10, 7, v0
	v_lshrrev_b32_e32 v23, 8, v4
	v_or_b32_e32 v4, 0xe00, v0
	s_movk_i32 s0, 0x100
	s_add_u32 s12, s76, 0x1ce33400
	v_lshrrev_b32_e32 v15, 8, v0
	v_lshrrev_b32_e32 v26, 8, v4
	v_lshl_add_u32 v4, v10, 4, 0
	v_cmp_gt_u32_e64 s[4:5], s0, v0
	s_mov_b32 s11, 0
	v_lshl_add_u32 v3, v0, 2, 0
	s_addc_u32 s13, s77, 0
	s_movk_i32 s0, 0x7f
	v_lshrrev_b32_e32 v2, 6, v0
	v_and_b32_e32 v14, 15, v0
	v_lshl_add_u32 v2, v2, 4, v14
	v_lshrrev_b32_e32 v14, 2, v0
	v_and_b32_e32 v14, 12, v14
	v_lshl_add_u32 v16, v15, 2, v8
	v_lshl_add_u32 v18, v17, 2, v8
	v_or_b32_e32 v19, 4, v15
	v_lshl_add_u32 v21, v20, 2, v8
	v_or_b32_e32 v22, 8, v15
	v_lshl_add_u32 v24, v23, 2, v8
	v_or_b32_e32 v25, 12, v15
	v_lshl_add_u32 v27, v26, 2, v8
	v_and_b32_e32 v28, 63, v0
	v_lshl_add_u32 v28, v28, 2, 0
	v_add_u32_e32 v28, 0x400, v28
	s_mov_b32 s1, 0x1bd33400
	v_lshlrev_b32_e32 v29, 2, v2
	v_lshl_add_u32 v29, v14, 7, v29
	s_mov_b32 s18, 0x200000
	s_mov_b32 s19, 0x400000
	s_mov_b32 s20, 0x600000
	s_movk_i32 s21, 0x1000
	s_mov_b32 s22, 0x1cd33400
	s_movk_i32 s23, 0x7e
	s_movk_i32 s24, 0x7d
	s_movk_i32 s25, 0x7c
	s_mov_b32 s26, s78

.LBB0_583:
	s_and_b64 s[16:17], s[14:15], exec
	s_cselect_b32 s17, s7, s9
	s_cselect_b32 s16, s6, s8
	global_load_dword v94, v29, s[16:17]
	global_load_dword v95, v29, s[16:17] offset:2048
	s_add_u32 s16, s16, 0x1000
	s_addc_u32 s17, s17, 0
	global_load_dword v96, v29, s[16:17]
	global_load_dword v97, v29, s[16:17] offset:2048
	s_add_u32 s16, s16, 0x1000
	s_addc_u32 s17, s17, 0
	global_load_dword v98, v29, s[16:17]
	global_load_dword v99, v29, s[16:17] offset:2048
	s_add_u32 s16, s16, 0x1000
	s_addc_u32 s17, s17, 0
	global_load_dword v100, v29, s[16:17]
	global_load_dword v101, v29, s[16:17] offset:2048
	s_add_u32 s16, s16, 0x1000
	s_addc_u32 s17, s17, 0
	global_load_dword v102, v29, s[16:17]
	global_load_dword v103, v29, s[16:17] offset:2048
	s_add_u32 s16, s16, 0x1000
	s_addc_u32 s17, s17, 0
	global_load_dword v104, v29, s[16:17]
	global_load_dword v105, v29, s[16:17] offset:2048
	s_add_u32 s16, s16, 0x1000
	s_addc_u32 s17, s17, 0
	global_load_dword v106, v29, s[16:17]
	global_load_dword v107, v29, s[16:17] offset:2048
	s_add_u32 s16, s16, 0x1000
	s_addc_u32 s17, s17, 0
	global_load_dword v108, v29, s[16:17]
	global_load_dword v109, v29, s[16:17] offset:2048
	s_add_u32 s16, s16, 0x1000
	s_addc_u32 s17, s17, 0
	global_load_dword v110, v29, s[16:17]
	global_load_dword v111, v29, s[16:17] offset:2048
	s_add_u32 s16, s16, 0x1000
	s_addc_u32 s17, s17, 0
	global_load_dword v112, v29, s[16:17]
	global_load_dword v113, v29, s[16:17] offset:2048
	s_add_u32 s16, s16, 0x1000
	s_addc_u32 s17, s17, 0
	global_load_dword v114, v29, s[16:17]
	global_load_dword v115, v29, s[16:17] offset:2048
	s_add_u32 s16, s16, 0x1000
	s_addc_u32 s17, s17, 0
	global_load_dword v116, v29, s[16:17]
	global_load_dword v117, v29, s[16:17] offset:2048
	s_add_u32 s16, s16, 0x1000
	s_addc_u32 s17, s17, 0
	global_load_dword v118, v29, s[16:17]
	global_load_dword v119, v29, s[16:17] offset:2048
	s_add_u32 s16, s16, 0x1000
	s_addc_u32 s17, s17, 0
	global_load_dword v120, v29, s[16:17]
	global_load_dword v121, v29, s[16:17] offset:2048
	s_add_u32 s16, s16, 0x1000
	s_addc_u32 s17, s17, 0
	global_load_dword v122, v29, s[16:17]
	global_load_dword v123, v29, s[16:17] offset:2048
	s_add_u32 s16, s16, 0x1000
	s_addc_u32 s17, s17, 0
	global_load_dword v124, v29, s[16:17]
	global_load_dword v125, v29, s[16:17] offset:2048
	s_add_u32 s16, s16, 0x1000
	s_addc_u32 s17, s17, 0
	global_load_dword v126, v29, s[16:17]
	global_load_dword v127, v29, s[16:17] offset:2048
	s_add_u32 s16, s16, 0x1000
	s_addc_u32 s17, s17, 0
	global_load_dword v128, v29, s[16:17]
	global_load_dword v129, v29, s[16:17] offset:2048
	s_add_u32 s16, s16, 0x1000
	s_addc_u32 s17, s17, 0
	global_load_dword v130, v29, s[16:17]
	global_load_dword v131, v29, s[16:17] offset:2048
	s_add_u32 s16, s16, 0x1000
	s_addc_u32 s17, s17, 0
	global_load_dword v132, v29, s[16:17]
	global_load_dword v133, v29, s[16:17] offset:2048
	s_add_u32 s16, s16, 0x1000
	s_addc_u32 s17, s17, 0
	global_load_dword v134, v29, s[16:17]
	global_load_dword v135, v29, s[16:17] offset:2048
	s_add_u32 s16, s16, 0x1000
	s_addc_u32 s17, s17, 0
	global_load_dword v136, v29, s[16:17]
	global_load_dword v137, v29, s[16:17] offset:2048
	s_add_u32 s16, s16, 0x1000
	s_addc_u32 s17, s17, 0
	global_load_dword v138, v29, s[16:17]
	global_load_dword v139, v29, s[16:17] offset:2048
	s_add_u32 s16, s16, 0x1000
	s_addc_u32 s17, s17, 0
	global_load_dword v140, v29, s[16:17]
	global_load_dword v141, v29, s[16:17] offset:2048
	s_add_u32 s16, s16, 0x1000
	s_addc_u32 s17, s17, 0
	global_load_dword v142, v29, s[16:17]
	global_load_dword v143, v29, s[16:17] offset:2048
	s_add_u32 s16, s16, 0x1000
	s_addc_u32 s17, s17, 0
	global_load_dword v144, v29, s[16:17]
	global_load_dword v145, v29, s[16:17] offset:2048
	s_add_u32 s16, s16, 0x1000
	s_addc_u32 s17, s17, 0
	global_load_dword v146, v29, s[16:17]
	global_load_dword v147, v29, s[16:17] offset:2048
	s_add_u32 s16, s16, 0x1000
	s_addc_u32 s17, s17, 0
	global_load_dword v148, v29, s[16:17]
	global_load_dword v149, v29, s[16:17] offset:2048
	s_add_u32 s16, s16, 0x1000
	s_addc_u32 s17, s17, 0
	global_load_dword v150, v29, s[16:17]
	global_load_dword v151, v29, s[16:17] offset:2048
	s_add_u32 s16, s16, 0x1000
	s_addc_u32 s17, s17, 0
	global_load_dword v152, v29, s[16:17]
	global_load_dword v153, v29, s[16:17] offset:2048
	s_add_u32 s16, s16, 0x1000
	s_addc_u32 s17, s17, 0
	s_waitcnt lgkmcnt(0)
	s_barrier
	ds_read_b32 v30, v28
	ds_read_b32 v31, v28 offset:256
	ds_read_b32 v32, v28 offset:512
	ds_read_b32 v33, v28 offset:768
	ds_read_b32 v34, v28 offset:1024
	ds_read_b32 v35, v28 offset:1280
	ds_read_b32 v36, v28 offset:1536
	ds_read_b32 v37, v28 offset:1792
	ds_read_b32 v38, v28 offset:2048
	ds_read_b32 v39, v28 offset:2304
	ds_read_b32 v40, v28 offset:2560
	ds_read_b32 v41, v28 offset:2816
	ds_read_b32 v42, v28 offset:3072
	ds_read_b32 v43, v28 offset:3328
	ds_read_b32 v44, v28 offset:3584
	ds_read_b32 v45, v28 offset:3840
	ds_read_b32 v46, v28 offset:4096
	ds_read_b32 v47, v28 offset:4352
	ds_read_b32 v48, v28 offset:4608
	ds_read_b32 v49, v28 offset:4864
	ds_read_b32 v50, v28 offset:5120
	ds_read_b32 v51, v28 offset:5376
	ds_read_b32 v52, v28 offset:5632
	ds_read_b32 v53, v28 offset:5888
	ds_read_b32 v54, v28 offset:6144
	ds_read_b32 v55, v28 offset:6400
	ds_read_b32 v56, v28 offset:6656
	ds_read_b32 v57, v28 offset:6912
	ds_read_b32 v58, v28 offset:7168
	ds_read_b32 v59, v28 offset:7424
	ds_read_b32 v60, v28 offset:7680
	ds_read_b32 v61, v28 offset:7936
	s_waitcnt vmcnt(59) lgkmcnt(15)
	v_mfma_f32_16x16x4_f32 v[62:65], v30, v94, 0
	s_waitcnt vmcnt(58) lgkmcnt(15)
	v_mfma_f32_16x16x4_f32 v[66:69], v31, v95, 0
	s_waitcnt vmcnt(57) lgkmcnt(15)
	v_mfma_f32_16x16x4_f32 v[70:73], v32, v96, 0
	s_waitcnt vmcnt(56) lgkmcnt(15)
	v_mfma_f32_16x16x4_f32 v[74:77], v33, v97, 0
	global_load_dword v154, v29, s[16:17]
	global_load_dword v155, v29, s[16:17] offset:2048
	s_add_u32 s16, s16, 0x1000
	s_addc_u32 s17, s17, 0
	global_load_dword v156, v29, s[16:17]
	global_load_dword v157, v29, s[16:17] offset:2048
	s_waitcnt vmcnt(59) lgkmcnt(15)
	v_mfma_f32_16x16x4_f32 v[62:65], v34, v98, v[62:65]
	s_waitcnt vmcnt(58) lgkmcnt(15)
	v_mfma_f32_16x16x4_f32 v[66:69], v35, v99, v[66:69]
	s_waitcnt vmcnt(57) lgkmcnt(15)
	v_mfma_f32_16x16x4_f32 v[70:73], v36, v100, v[70:73]
	s_waitcnt vmcnt(56) lgkmcnt(15)
	v_mfma_f32_16x16x4_f32 v[74:77], v37, v101, v[74:77]
	s_waitcnt vmcnt(55) lgkmcnt(15)
	v_mfma_f32_16x16x4_f32 v[62:65], v38, v102, v[62:65]
	s_waitcnt vmcnt(54) lgkmcnt(15)
	v_mfma_f32_16x16x4_f32 v[66:69], v39, v103, v[66:69]
	s_waitcnt vmcnt(53) lgkmcnt(15)
	v_mfma_f32_16x16x4_f32 v[70:73], v40, v104, v[70:73]
	s_waitcnt vmcnt(52) lgkmcnt(15)
	v_mfma_f32_16x16x4_f32 v[74:77], v41, v105, v[74:77]
	s_waitcnt vmcnt(51) lgkmcnt(15)
	v_mfma_f32_16x16x4_f32 v[62:65], v42, v106, v[62:65]
	s_waitcnt vmcnt(50) lgkmcnt(15)
	v_mfma_f32_16x16x4_f32 v[66:69], v43, v107, v[66:69]
	s_waitcnt vmcnt(49) lgkmcnt(15)
	v_mfma_f32_16x16x4_f32 v[70:73], v44, v108, v[70:73]
	s_waitcnt vmcnt(48) lgkmcnt(15)
	v_mfma_f32_16x16x4_f32 v[74:77], v45, v109, v[74:77]
	ds_read_b32 v30, v28 offset:8192
	ds_read_b32 v31, v28 offset:8448
	ds_read_b32 v32, v28 offset:8704
	ds_read_b32 v33, v28 offset:8960
	ds_read_b32 v34, v28 offset:9216
	ds_read_b32 v35, v28 offset:9472
	ds_read_b32 v36, v28 offset:9728
	ds_read_b32 v37, v28 offset:9984
	ds_read_b32 v38, v28 offset:10240
	ds_read_b32 v39, v28 offset:10496
	ds_read_b32 v40, v28 offset:10752
	ds_read_b32 v41, v28 offset:11008
	ds_read_b32 v42, v28 offset:11264
	ds_read_b32 v43, v28 offset:11520
	ds_read_b32 v44, v28 offset:11776
	ds_read_b32 v45, v28 offset:12032
	s_waitcnt vmcnt(47) lgkmcnt(15)
	v_mfma_f32_16x16x4_f32 v[62:65], v46, v110, v[62:65]
	s_waitcnt vmcnt(46) lgkmcnt(15)
	v_mfma_f32_16x16x4_f32 v[66:69], v47, v111, v[66:69]
	s_waitcnt vmcnt(45) lgkmcnt(15)
	v_mfma_f32_16x16x4_f32 v[70:73], v48, v112, v[70:73]
	s_waitcnt vmcnt(44) lgkmcnt(15)
	v_mfma_f32_16x16x4_f32 v[74:77], v49, v113, v[74:77]
	s_waitcnt vmcnt(43) lgkmcnt(15)
	v_mfma_f32_16x16x4_f32 v[62:65], v50, v114, v[62:65]
	s_waitcnt vmcnt(42) lgkmcnt(15)
	v_mfma_f32_16x16x4_f32 v[66:69], v51, v115, v[66:69]
	s_waitcnt vmcnt(41) lgkmcnt(15)
	v_mfma_f32_16x16x4_f32 v[70:73], v52, v116, v[70:73]
	s_waitcnt vmcnt(40) lgkmcnt(15)
	v_mfma_f32_16x16x4_f32 v[74:77], v53, v117, v[74:77]
	s_waitcnt vmcnt(39) lgkmcnt(15)
	v_mfma_f32_16x16x4_f32 v[62:65], v54, v118, v[62:65]
	s_waitcnt vmcnt(38) lgkmcnt(15)
	v_mfma_f32_16x16x4_f32 v[66:69], v55, v119, v[66:69]
	s_waitcnt vmcnt(37) lgkmcnt(15)
	v_mfma_f32_16x16x4_f32 v[70:73], v56, v120, v[70:73]
	s_waitcnt vmcnt(36) lgkmcnt(15)
	v_mfma_f32_16x16x4_f32 v[74:77], v57, v121, v[74:77]
	s_waitcnt vmcnt(35) lgkmcnt(15)
	v_mfma_f32_16x16x4_f32 v[62:65], v58, v122, v[62:65]
	s_waitcnt vmcnt(34) lgkmcnt(15)
	v_mfma_f32_16x16x4_f32 v[66:69], v59, v123, v[66:69]
	s_waitcnt vmcnt(33) lgkmcnt(15)
	v_mfma_f32_16x16x4_f32 v[70:73], v60, v124, v[70:73]
	s_waitcnt vmcnt(32) lgkmcnt(15)
	v_mfma_f32_16x16x4_f32 v[74:77], v61, v125, v[74:77]
	ds_read_b32 v46, v28 offset:12288
	ds_read_b32 v47, v28 offset:12544
	ds_read_b32 v48, v28 offset:12800
	ds_read_b32 v49, v28 offset:13056
	ds_read_b32 v50, v28 offset:13312
	ds_read_b32 v51, v28 offset:13568
	ds_read_b32 v52, v28 offset:13824
	ds_read_b32 v53, v28 offset:14080
	ds_read_b32 v54, v28 offset:14336
	ds_read_b32 v55, v28 offset:14592
	ds_read_b32 v56, v28 offset:14848
	ds_read_b32 v57, v28 offset:15104
	ds_read_b32 v58, v28 offset:15360
	ds_read_b32 v59, v28 offset:15616
	ds_read_b32 v60, v28 offset:15872
	ds_read_b32 v61, v28 offset:16128
	s_waitcnt vmcnt(31) lgkmcnt(15)
	v_mfma_f32_16x16x4_f32 v[62:65], v30, v126, v[62:65]
	s_waitcnt vmcnt(30) lgkmcnt(15)
	v_mfma_f32_16x16x4_f32 v[66:69], v31, v127, v[66:69]
	s_waitcnt vmcnt(29) lgkmcnt(15)
	v_mfma_f32_16x16x4_f32 v[70:73], v32, v128, v[70:73]
	s_waitcnt vmcnt(28) lgkmcnt(15)
	v_mfma_f32_16x16x4_f32 v[74:77], v33, v129, v[74:77]
	s_waitcnt vmcnt(27) lgkmcnt(15)
	v_mfma_f32_16x16x4_f32 v[62:65], v34, v130, v[62:65]
	s_waitcnt vmcnt(26) lgkmcnt(15)
	v_mfma_f32_16x16x4_f32 v[66:69], v35, v131, v[66:69]
	s_waitcnt vmcnt(25) lgkmcnt(15)
	v_mfma_f32_16x16x4_f32 v[70:73], v36, v132, v[70:73]
	s_waitcnt vmcnt(24) lgkmcnt(15)
	v_mfma_f32_16x16x4_f32 v[74:77], v37, v133, v[74:77]
	s_waitcnt vmcnt(23) lgkmcnt(15)
	v_mfma_f32_16x16x4_f32 v[62:65], v38, v134, v[62:65]
	s_waitcnt vmcnt(22) lgkmcnt(15)
	v_mfma_f32_16x16x4_f32 v[66:69], v39, v135, v[66:69]
	s_waitcnt vmcnt(21) lgkmcnt(15)
	v_mfma_f32_16x16x4_f32 v[70:73], v40, v136, v[70:73]
	s_waitcnt vmcnt(20) lgkmcnt(15)
	v_mfma_f32_16x16x4_f32 v[74:77], v41, v137, v[74:77]
	s_waitcnt vmcnt(19) lgkmcnt(15)
	v_mfma_f32_16x16x4_f32 v[62:65], v42, v138, v[62:65]
	s_waitcnt vmcnt(18) lgkmcnt(15)
	v_mfma_f32_16x16x4_f32 v[66:69], v43, v139, v[66:69]
	s_waitcnt vmcnt(17) lgkmcnt(15)
	v_mfma_f32_16x16x4_f32 v[70:73], v44, v140, v[70:73]
	s_waitcnt vmcnt(16) lgkmcnt(15)
	v_mfma_f32_16x16x4_f32 v[74:77], v45, v141, v[74:77]
	s_waitcnt vmcnt(15) lgkmcnt(15)
	v_mfma_f32_16x16x4_f32 v[62:65], v46, v142, v[62:65]
	s_waitcnt vmcnt(14) lgkmcnt(14)
	v_mfma_f32_16x16x4_f32 v[66:69], v47, v143, v[66:69]
	s_waitcnt vmcnt(13) lgkmcnt(13)
	v_mfma_f32_16x16x4_f32 v[70:73], v48, v144, v[70:73]
	s_waitcnt vmcnt(12) lgkmcnt(12)
	v_mfma_f32_16x16x4_f32 v[74:77], v49, v145, v[74:77]
	s_waitcnt vmcnt(11) lgkmcnt(11)
	v_mfma_f32_16x16x4_f32 v[62:65], v50, v146, v[62:65]
	s_waitcnt vmcnt(10) lgkmcnt(10)
	v_mfma_f32_16x16x4_f32 v[66:69], v51, v147, v[66:69]
	s_waitcnt vmcnt(9) lgkmcnt(9)
	v_mfma_f32_16x16x4_f32 v[70:73], v52, v148, v[70:73]
	s_waitcnt vmcnt(8) lgkmcnt(8)
	v_mfma_f32_16x16x4_f32 v[74:77], v53, v149, v[74:77]
	s_waitcnt vmcnt(7) lgkmcnt(7)
	v_mfma_f32_16x16x4_f32 v[62:65], v54, v150, v[62:65]
	s_waitcnt vmcnt(6) lgkmcnt(6)
	v_mfma_f32_16x16x4_f32 v[66:69], v55, v151, v[66:69]
	s_waitcnt vmcnt(5) lgkmcnt(5)
	v_mfma_f32_16x16x4_f32 v[70:73], v56, v152, v[70:73]
	s_waitcnt vmcnt(4) lgkmcnt(4)
	v_mfma_f32_16x16x4_f32 v[74:77], v57, v153, v[74:77]
	s_waitcnt vmcnt(3) lgkmcnt(3)
	v_mfma_f32_16x16x4_f32 v[62:65], v58, v154, v[62:65]
	s_waitcnt vmcnt(2) lgkmcnt(2)
	v_mfma_f32_16x16x4_f32 v[66:69], v59, v155, v[66:69]
	s_waitcnt vmcnt(1) lgkmcnt(1)
	v_mfma_f32_16x16x4_f32 v[70:73], v60, v156, v[70:73]
	s_waitcnt vmcnt(0) lgkmcnt(0)
	v_mfma_f32_16x16x4_f32 v[74:77], v61, v157, v[74:77]
	s_nop 15
	s_nop 3
	v_add_f32_e32 v12, v62, v66
	v_add_f32_e32 v4, v70, v74
	s_nop 0
	v_add_f32_e32 v12, v12, v4
	v_add_f32_e32 v13, v63, v67
	v_add_f32_e32 v4, v71, v75
	s_nop 0
	v_add_f32_e32 v13, v13, v4
	v_add_f32_e32 v10, v64, v68
	v_add_f32_e32 v4, v72, v76
	s_nop 0
	v_add_f32_e32 v10, v10, v4
	v_add_f32_e32 v11, v65, v69
	v_add_f32_e32 v4, v73, v77
	s_nop 0
	v_add_f32_e32 v11, v11, v4
	s_and_b64 s[14:15], s[14:15], exec
	s_cselect_b32 s10, s22, 0x1cdb3400
	s_add_u32 s14, s76, s10
	v_add_u32_e32 v30, s27, v14
	s_addc_u32 s15, s77, 0
	v_add_lshl_u32 v4, v30, s28, 8
	v_lshl_add_u64 v[8:9], s[14:15], 0, v[4:5]
	v_lshlrev_b32_e32 v4, 1, v2
	v_lshl_add_u64 v[8:9], v[8:9], 0, v[4:5]
	v_cvt_pk_bf16_f32 v4, v12, s0
	v_cmp_gt_u32_e32 vcc, s0, v30
	s_add_i32 s26, s26, s79
	s_cmpk_gt_i32 s26, 0xff
	v_cndmask_b32_e32 v4, 0, v4, vcc
	global_store_short v[8:9], v4, off
	v_cvt_pk_bf16_f32 v4, v13, s0
	v_cmp_gt_u32_e32 vcc, s23, v30
	s_nop 1
	v_cndmask_b32_e32 v4, 0, v4, vcc
	global_store_short v[8:9], v4, off offset:256
	v_cvt_pk_bf16_f32 v4, v10, s0
	v_cmp_gt_u32_e32 vcc, s24, v30
	s_nop 1
	v_cndmask_b32_e32 v4, 0, v4, vcc
	global_store_short v[8:9], v4, off offset:512
	v_cvt_pk_bf16_f32 v4, v11, s0
	v_cmp_gt_u32_e32 vcc, s25, v30
	s_nop 1
	v_cndmask_b32_e32 v4, 0, v4, vcc
	global_store_short v[8:9], v4, off offset:768
	s_barrier
	s_cbranch_scc0 .LBB0_573
